# EpiFox q/k tiles: per-head sum-of-squares cross-lane steps via v_permlane16_swap/v_permlane32_swap instead of ds_bpermute round trips (bit-identical)
# speedup vs baseline: 1.0188x; 1.0188x over previous
;     __device__ __forceinline__ void operator()(const f32x4 (&acc)[2][2][4][2], const Unit& u, int wr, int wc, int fr, int fq, PG8_LAS unsigned char* lds, int& rs_pm, int& rs_tog) const {
;     ...
;                 if (sec < 2) {
;                     float q = 0.f;
; #pragma unroll
;                     for (int bj = 0; bj < 2; ++bj)
; #pragma unroll
;                         for (int n = 0; n < 2; ++n) q += (x[bj][n][0] * x[bj][n][0] + x[bj][n][1] * x[bj][n][1]) + (x[bj][n][2] * x[bj][n][2] + x[bj][n][3] * x[bj][n][3]);
;                     q += __shfl_xor(q, 16); q += __shfl_xor(q, 32);
;                     const float rn = __builtin_amdgcn_rsqf(q * (1.0f / 64.0f) + kEps);
; #pragma unroll
;                     for (int bj = 0; bj < 2; ++bj)
; #pragma unroll
;                         for (int n = 0; n < 2; ++n) x[bj][n] = x[bj][n] * rn * gn[bj][n];
.LBB0_154:
	s_andn2_b64 vcc, exec, s[82:83]
	s_cbranch_vccnz .LBB0_156
	v_pk_mul_f32 v[124:125], v[120:121], v[120:121]
	v_pk_mul_f32 v[128:129], v[162:163], v[162:163]
	v_mul_f32_e32 v0, v126, v126
	v_pk_mov_b32 v[164:165], v[128:129], v[124:125] op_sel:[1,0]
	v_mov_b32_e32 v129, v125
	v_pk_add_f32 v[124:125], v[164:165], v[128:129]
	v_pk_mul_f32 v[128:129], v[118:119], v[118:119]
	v_pk_mul_f32 v[164:165], v[160:161], v[160:161]
	v_pk_add_f32 v[124:125], v[124:125], v[124:125] op_sel_hi:[0,1]
	v_pk_mov_b32 v[166:167], v[164:165], v[128:129] op_sel:[1,0]
	v_mov_b32_e32 v165, v129
	v_pk_add_f32 v[128:129], v[166:167], v[164:165]
	v_pk_fma_f32 v[164:165], v[126:127], v[126:127], v[0:1] op_sel_hi:[1,1,0]
	v_mul_f32_e32 v0, v116, v116
	v_pk_add_f32 v[128:129], v[128:129], v[128:129] op_sel_hi:[0,1]
	v_pk_fma_f32 v[166:167], v[116:117], v[116:117], v[0:1] op_sel_hi:[1,1,0]
	v_mul_f32_e32 v164, v122, v122
	v_mul_f32_e32 v166, v123, v123
	v_mul_f32_e32 v124, v114, v114
	v_mul_f32_e32 v128, v115, v115
	v_pk_add_f32 v[164:165], v[164:165], v[166:167]
	v_pk_add_f32 v[124:125], v[124:125], v[128:129]
	s_nop 0
	v_pk_add_f32 v[124:125], v[164:165], v[124:125]
	s_nop 0
	v_add_f32_e32 v0, v124, v125
	v_mov_b32_e32 v124, v0
	s_nop 1
	v_permlane16_swap_b32_e32 v124, v0
	s_nop 1
	v_add_f32_e32 v0, v0, v124
	v_mov_b32_e32 v124, v0
	s_nop 1
	v_permlane32_swap_b32_e32 v124, v0
	s_nop 1
	v_add_f32_e32 v0, v0, v124
	v_fmamk_f32 v0, v0, 0x3c800000, v232
	v_rsq_f32_e32 v0, v0
	s_nop 0
	v_pk_mul_f32 v[120:121], v[120:121], v[0:1] op_sel_hi:[1,0]
	v_pk_mul_f32 v[118:119], v[118:119], v[0:1] op_sel_hi:[1,0]
	v_pk_mul_f32 v[116:117], v[116:117], v[0:1] op_sel_hi:[1,0]
	v_pk_mul_f32 v[128:129], v[162:163], v[0:1] op_sel_hi:[1,0]
	v_pk_mul_f32 v[124:125], v[158:159], v[120:121]
	v_pk_mul_f32 v[120:121], v[160:161], v[0:1] op_sel_hi:[1,0]
	v_pk_mul_f32 v[164:165], v[154:155], v[118:119]
	v_pk_mul_f32 v[118:119], v[126:127], v[0:1] op_sel_hi:[1,0]
	v_pk_mul_f32 v[168:169], v[150:151], v[116:117]
	v_pk_mul_f32 v[116:117], v[122:123], v[0:1] op_sel_hi:[1,0]
	v_pk_mul_f32 v[114:115], v[114:115], v[0:1] op_sel_hi:[1,0]
	v_pk_mul_f32 v[128:129], v[156:157], v[128:129]
	v_pk_mul_f32 v[166:167], v[152:153], v[120:121]
	v_pk_mul_f32 v[170:171], v[148:149], v[118:119]
	v_pk_mul_f32 v[172:173], v[146:147], v[114:115]
	v_pk_mul_f32 v[174:175], v[144:145], v[116:117]

;     __device__ __forceinline__ void operator()(const f32x4 (&acc)[2][2][4][2], const Unit& u, int wr, int wc, int fr, int fq, PG8_LAS unsigned char* lds, int& rs_pm, int& rs_tog) const {
;     ...
;                     float q = 0.f;
; #pragma unroll
;                     for (int bj = 0; bj < 2; ++bj)
; #pragma unroll
;                         for (int n = 0; n < 2; ++n) q += (x[bj][n][0] * x[bj][n][0] + x[bj][n][1] * x[bj][n][1]) + (x[bj][n][2] * x[bj][n][2] + x[bj][n][3] * x[bj][n][3]);
;                     q += __shfl_xor(q, 16); q += __shfl_xor(q, 32);
;                     const float rn = __builtin_amdgcn_rsqf(q * (1.0f / 64.0f) + kEps);
; #pragma unroll
;                     for (int bj = 0; bj < 2; ++bj)
; #pragma unroll
;                         for (int n = 0; n < 2; ++n) x[bj][n] = x[bj][n] * rn * gn[bj][n];
.LBB0_160:
	s_andn2_b64 vcc, exec, s[80:81]
	s_cbranch_vccnz .LBB0_162
	v_pk_mul_f32 v[108:109], v[104:105], v[104:105]
	v_pk_mul_f32 v[112:113], v[120:121], v[120:121]
	v_mul_f32_e32 v0, v110, v110
	v_pk_mov_b32 v[122:123], v[112:113], v[108:109] op_sel:[1,0]
	v_mov_b32_e32 v113, v109
	v_pk_add_f32 v[108:109], v[122:123], v[112:113]
	v_pk_mul_f32 v[112:113], v[102:103], v[102:103]
	v_pk_mul_f32 v[122:123], v[118:119], v[118:119]
	v_pk_add_f32 v[108:109], v[108:109], v[108:109] op_sel_hi:[0,1]
	v_pk_mov_b32 v[124:125], v[122:123], v[112:113] op_sel:[1,0]
	v_mov_b32_e32 v123, v113
	v_pk_add_f32 v[112:113], v[124:125], v[122:123]
	v_pk_fma_f32 v[122:123], v[110:111], v[110:111], v[0:1] op_sel_hi:[1,1,0]
	v_mul_f32_e32 v0, v100, v100
	v_pk_add_f32 v[112:113], v[112:113], v[112:113] op_sel_hi:[0,1]
	v_pk_fma_f32 v[124:125], v[100:101], v[100:101], v[0:1] op_sel_hi:[1,1,0]
	v_mul_f32_e32 v122, v106, v106
	v_mul_f32_e32 v124, v107, v107
	v_mul_f32_e32 v108, v98, v98
	v_mul_f32_e32 v112, v99, v99
	v_pk_add_f32 v[122:123], v[122:123], v[124:125]
	v_pk_add_f32 v[108:109], v[108:109], v[112:113]
	s_nop 0
	v_pk_add_f32 v[108:109], v[122:123], v[108:109]
	s_nop 0
	v_add_f32_e32 v0, v108, v109
	v_mov_b32_e32 v108, v0
	s_nop 1
	v_permlane16_swap_b32_e32 v108, v0
	s_nop 1
	v_add_f32_e32 v0, v0, v108
	v_mov_b32_e32 v108, v0
	s_nop 1
	v_permlane32_swap_b32_e32 v108, v0
	s_nop 1
	v_add_f32_e32 v0, v0, v108
	v_fmamk_f32 v0, v0, 0x3c800000, v232
	v_rsq_f32_e32 v0, v0
	s_nop 0
	v_pk_mul_f32 v[104:105], v[104:105], v[0:1] op_sel_hi:[1,0]
	v_pk_mul_f32 v[102:103], v[102:103], v[0:1] op_sel_hi:[1,0]
	v_pk_mul_f32 v[100:101], v[100:101], v[0:1] op_sel_hi:[1,0]
	v_pk_mul_f32 v[112:113], v[120:121], v[0:1] op_sel_hi:[1,0]
	v_pk_mul_f32 v[108:109], v[158:159], v[104:105]
	v_pk_mul_f32 v[104:105], v[118:119], v[0:1] op_sel_hi:[1,0]
	v_pk_mul_f32 v[122:123], v[154:155], v[102:103]
	v_pk_mul_f32 v[102:103], v[110:111], v[0:1] op_sel_hi:[1,0]
	v_pk_mul_f32 v[126:127], v[150:151], v[100:101]
	v_pk_mul_f32 v[100:101], v[106:107], v[0:1] op_sel_hi:[1,0]
	v_pk_mul_f32 v[98:99], v[98:99], v[0:1] op_sel_hi:[1,0]
	v_pk_mul_f32 v[112:113], v[156:157], v[112:113]
	v_pk_mul_f32 v[124:125], v[152:153], v[104:105]
	v_pk_mul_f32 v[128:129], v[148:149], v[102:103]
	v_pk_mul_f32 v[160:161], v[146:147], v[98:99]
	v_pk_mul_f32 v[162:163], v[144:145], v[100:101]

;     __device__ __forceinline__ void operator()(const f32x4 (&acc)[2][2][4][2], const Unit& u, int wr, int wc, int fr, int fq, PG8_LAS unsigned char* lds, int& rs_pm, int& rs_tog) const {
;     ...
;                     float q = 0.f;
; #pragma unroll
;                     for (int bj = 0; bj < 2; ++bj)
; #pragma unroll
;                         for (int n = 0; n < 2; ++n) q += (x[bj][n][0] * x[bj][n][0] + x[bj][n][1] * x[bj][n][1]) + (x[bj][n][2] * x[bj][n][2] + x[bj][n][3] * x[bj][n][3]);
;                     q += __shfl_xor(q, 16); q += __shfl_xor(q, 32);
;                     const float rn = __builtin_amdgcn_rsqf(q * (1.0f / 64.0f) + kEps);
; #pragma unroll
;                     for (int bj = 0; bj < 2; ++bj)
; #pragma unroll
;                         for (int n = 0; n < 2; ++n) x[bj][n] = x[bj][n] * rn * gn[bj][n];
.LBB0_166:
	s_andn2_b64 vcc, exec, s[80:81]
	s_cbranch_vccnz .LBB0_168
	v_pk_mul_f32 v[92:93], v[88:89], v[88:89]
	v_pk_mul_f32 v[96:97], v[100:101], v[100:101]
	v_mul_f32_e32 v0, v94, v94
	v_pk_mov_b32 v[102:103], v[96:97], v[92:93] op_sel:[1,0]
	v_mov_b32_e32 v97, v93
	v_pk_add_f32 v[92:93], v[102:103], v[96:97]
	v_pk_mul_f32 v[96:97], v[86:87], v[86:87]
	v_pk_mul_f32 v[102:103], v[98:99], v[98:99]
	v_pk_add_f32 v[92:93], v[92:93], v[92:93] op_sel_hi:[0,1]
	v_pk_mov_b32 v[104:105], v[102:103], v[96:97] op_sel:[1,0]
	v_mov_b32_e32 v103, v97
	v_pk_add_f32 v[96:97], v[104:105], v[102:103]
	v_pk_fma_f32 v[102:103], v[94:95], v[94:95], v[0:1] op_sel_hi:[1,1,0]
	v_mul_f32_e32 v0, v84, v84
	v_pk_add_f32 v[96:97], v[96:97], v[96:97] op_sel_hi:[0,1]
	v_pk_fma_f32 v[104:105], v[84:85], v[84:85], v[0:1] op_sel_hi:[1,1,0]
	v_mul_f32_e32 v102, v90, v90
	v_mul_f32_e32 v104, v91, v91
	v_mul_f32_e32 v92, v82, v82
	v_mul_f32_e32 v96, v83, v83
	v_pk_add_f32 v[102:103], v[102:103], v[104:105]
	v_pk_add_f32 v[92:93], v[92:93], v[96:97]
	s_nop 0
	v_pk_add_f32 v[92:93], v[102:103], v[92:93]
	s_nop 0
	v_add_f32_e32 v0, v92, v93
	v_mov_b32_e32 v92, v0
	s_nop 1
	v_permlane16_swap_b32_e32 v92, v0
	s_nop 1
	v_add_f32_e32 v0, v0, v92
	v_mov_b32_e32 v92, v0
	s_nop 1
	v_permlane32_swap_b32_e32 v92, v0
	s_nop 1
	v_add_f32_e32 v0, v0, v92
	v_fmamk_f32 v0, v0, 0x3c800000, v232
	v_rsq_f32_e32 v0, v0
	s_nop 0
	v_pk_mul_f32 v[88:89], v[88:89], v[0:1] op_sel_hi:[1,0]
	v_pk_mul_f32 v[86:87], v[86:87], v[0:1] op_sel_hi:[1,0]
	v_pk_mul_f32 v[84:85], v[84:85], v[0:1] op_sel_hi:[1,0]
	v_pk_mul_f32 v[96:97], v[100:101], v[0:1] op_sel_hi:[1,0]
	v_pk_mul_f32 v[92:93], v[158:159], v[88:89]
	v_pk_mul_f32 v[88:89], v[98:99], v[0:1] op_sel_hi:[1,0]
	v_pk_mul_f32 v[102:103], v[154:155], v[86:87]
	v_pk_mul_f32 v[86:87], v[94:95], v[0:1] op_sel_hi:[1,0]
	v_pk_mul_f32 v[106:107], v[150:151], v[84:85]
	v_pk_mul_f32 v[84:85], v[90:91], v[0:1] op_sel_hi:[1,0]
	v_pk_mul_f32 v[82:83], v[82:83], v[0:1] op_sel_hi:[1,0]
	v_pk_mul_f32 v[96:97], v[156:157], v[96:97]
	v_pk_mul_f32 v[104:105], v[152:153], v[88:89]
	v_pk_mul_f32 v[108:109], v[148:149], v[86:87]
	v_pk_mul_f32 v[110:111], v[146:147], v[82:83]
	v_pk_mul_f32 v[112:113], v[144:145], v[84:85]

;     __device__ __forceinline__ void operator()(const f32x4 (&acc)[2][2][4][2], const Unit& u, int wr, int wc, int fr, int fq, PG8_LAS unsigned char* lds, int& rs_pm, int& rs_tog) const {
;     ...
;                     float q = 0.f;
; #pragma unroll
;                     for (int bj = 0; bj < 2; ++bj)
; #pragma unroll
;                         for (int n = 0; n < 2; ++n) q += (x[bj][n][0] * x[bj][n][0] + x[bj][n][1] * x[bj][n][1]) + (x[bj][n][2] * x[bj][n][2] + x[bj][n][3] * x[bj][n][3]);
;                     q += __shfl_xor(q, 16); q += __shfl_xor(q, 32);
;                     const float rn = __builtin_amdgcn_rsqf(q * (1.0f / 64.0f) + kEps);
; #pragma unroll
;                     for (int bj = 0; bj < 2; ++bj)
; #pragma unroll
;                         for (int n = 0; n < 2; ++n) x[bj][n] = x[bj][n] * rn * gn[bj][n];
.LBB0_172:
	s_andn2_b64 vcc, exec, s[80:81]
	s_cbranch_vccnz .LBB0_174
	v_pk_mul_f32 v[76:77], v[72:73], v[72:73]
	v_pk_mul_f32 v[80:81], v[84:85], v[84:85]
	v_mul_f32_e32 v0, v78, v78
	v_pk_mov_b32 v[86:87], v[80:81], v[76:77] op_sel:[1,0]
	v_mov_b32_e32 v81, v77
	v_pk_add_f32 v[76:77], v[86:87], v[80:81]
	v_pk_mul_f32 v[80:81], v[70:71], v[70:71]
	v_pk_mul_f32 v[86:87], v[82:83], v[82:83]
	v_pk_add_f32 v[76:77], v[76:77], v[76:77] op_sel_hi:[0,1]
	v_pk_mov_b32 v[88:89], v[86:87], v[80:81] op_sel:[1,0]
	v_mov_b32_e32 v87, v81
	v_pk_add_f32 v[80:81], v[88:89], v[86:87]
	v_pk_fma_f32 v[86:87], v[78:79], v[78:79], v[0:1] op_sel_hi:[1,1,0]
	v_mul_f32_e32 v0, v68, v68
	v_pk_add_f32 v[80:81], v[80:81], v[80:81] op_sel_hi:[0,1]
	v_pk_fma_f32 v[88:89], v[68:69], v[68:69], v[0:1] op_sel_hi:[1,1,0]
	v_mul_f32_e32 v86, v74, v74
	v_mul_f32_e32 v88, v75, v75
	v_mul_f32_e32 v76, v66, v66
	v_mul_f32_e32 v80, v67, v67
	v_pk_add_f32 v[86:87], v[86:87], v[88:89]
	v_pk_add_f32 v[76:77], v[76:77], v[80:81]
	s_nop 0
	v_pk_add_f32 v[76:77], v[86:87], v[76:77]
	s_nop 0
	v_add_f32_e32 v0, v76, v77
	v_mov_b32_e32 v76, v0
	s_nop 1
	v_permlane16_swap_b32_e32 v76, v0
	s_nop 1
	v_add_f32_e32 v0, v0, v76
	v_mov_b32_e32 v76, v0
	s_nop 1
	v_permlane32_swap_b32_e32 v76, v0
	s_nop 1
	v_add_f32_e32 v0, v0, v76
	v_fmamk_f32 v0, v0, 0x3c800000, v232
	v_rsq_f32_e32 v0, v0
	s_nop 0
	v_pk_mul_f32 v[72:73], v[72:73], v[0:1] op_sel_hi:[1,0]
	v_pk_mul_f32 v[70:71], v[70:71], v[0:1] op_sel_hi:[1,0]
	v_pk_mul_f32 v[68:69], v[68:69], v[0:1] op_sel_hi:[1,0]
	v_pk_mul_f32 v[80:81], v[84:85], v[0:1] op_sel_hi:[1,0]
	v_pk_mul_f32 v[76:77], v[158:159], v[72:73]
	v_pk_mul_f32 v[72:73], v[82:83], v[0:1] op_sel_hi:[1,0]
	v_pk_mul_f32 v[86:87], v[154:155], v[70:71]
	v_pk_mul_f32 v[70:71], v[78:79], v[0:1] op_sel_hi:[1,0]
	v_pk_mul_f32 v[90:91], v[150:151], v[68:69]
	v_pk_mul_f32 v[68:69], v[74:75], v[0:1] op_sel_hi:[1,0]
	v_pk_mul_f32 v[66:67], v[66:67], v[0:1] op_sel_hi:[1,0]
	v_pk_mul_f32 v[80:81], v[156:157], v[80:81]
	v_pk_mul_f32 v[88:89], v[152:153], v[72:73]
	v_pk_mul_f32 v[92:93], v[148:149], v[70:71]
	v_pk_mul_f32 v[94:95], v[146:147], v[66:67]
	v_pk_mul_f32 v[96:97], v[144:145], v[68:69]

;     __device__ __forceinline__ void operator()(const f32x4 (&acc)[2][2][4][2], const Unit& u, int wr, int wc, int fr, int fq, PG8_LAS unsigned char* lds, int& rs_pm, int& rs_tog) const {
;     ...
;                     float q = 0.f;
; #pragma unroll
;                     for (int bj = 0; bj < 2; ++bj)
; #pragma unroll
;                         for (int n = 0; n < 2; ++n) q += (x[bj][n][0] * x[bj][n][0] + x[bj][n][1] * x[bj][n][1]) + (x[bj][n][2] * x[bj][n][2] + x[bj][n][3] * x[bj][n][3]);
;                     q += __shfl_xor(q, 16); q += __shfl_xor(q, 32);
;                     const float rn = __builtin_amdgcn_rsqf(q * (1.0f / 64.0f) + kEps);
; #pragma unroll
;                     for (int bj = 0; bj < 2; ++bj)
; #pragma unroll
;                         for (int n = 0; n < 2; ++n) x[bj][n] = x[bj][n] * rn * gn[bj][n];
.LBB0_178:
	s_andn2_b64 vcc, exec, s[80:81]
	s_cbranch_vccnz .LBB0_180
	v_pk_mul_f32 v[60:61], v[56:57], v[56:57]
	v_pk_mul_f32 v[64:65], v[68:69], v[68:69]
	v_mul_f32_e32 v0, v62, v62
	v_pk_mov_b32 v[70:71], v[64:65], v[60:61] op_sel:[1,0]
	v_mov_b32_e32 v65, v61
	v_pk_add_f32 v[60:61], v[70:71], v[64:65]
	v_pk_mul_f32 v[64:65], v[54:55], v[54:55]
	v_pk_mul_f32 v[70:71], v[66:67], v[66:67]
	v_pk_add_f32 v[60:61], v[60:61], v[60:61] op_sel_hi:[0,1]
	v_pk_mov_b32 v[72:73], v[70:71], v[64:65] op_sel:[1,0]
	v_mov_b32_e32 v71, v65
	v_pk_add_f32 v[64:65], v[72:73], v[70:71]
	v_pk_fma_f32 v[70:71], v[62:63], v[62:63], v[0:1] op_sel_hi:[1,1,0]
	v_mul_f32_e32 v0, v52, v52
	v_pk_add_f32 v[64:65], v[64:65], v[64:65] op_sel_hi:[0,1]
	v_pk_fma_f32 v[72:73], v[52:53], v[52:53], v[0:1] op_sel_hi:[1,1,0]
	v_mul_f32_e32 v70, v58, v58
	v_mul_f32_e32 v72, v59, v59
	v_mul_f32_e32 v60, v50, v50
	v_mul_f32_e32 v64, v51, v51
	v_pk_add_f32 v[70:71], v[70:71], v[72:73]
	v_pk_add_f32 v[60:61], v[60:61], v[64:65]
	s_nop 0
	v_pk_add_f32 v[60:61], v[70:71], v[60:61]
	s_nop 0
	v_add_f32_e32 v0, v60, v61
	v_mov_b32_e32 v60, v0
	s_nop 1
	v_permlane16_swap_b32_e32 v60, v0
	s_nop 1
	v_add_f32_e32 v0, v0, v60
	v_mov_b32_e32 v60, v0
	s_nop 1
	v_permlane32_swap_b32_e32 v60, v0
	s_nop 1
	v_add_f32_e32 v0, v0, v60
	v_fmamk_f32 v0, v0, 0x3c800000, v232
	v_rsq_f32_e32 v0, v0
	s_nop 0
	v_pk_mul_f32 v[56:57], v[56:57], v[0:1] op_sel_hi:[1,0]
	v_pk_mul_f32 v[54:55], v[54:55], v[0:1] op_sel_hi:[1,0]
	v_pk_mul_f32 v[52:53], v[52:53], v[0:1] op_sel_hi:[1,0]
	v_pk_mul_f32 v[64:65], v[68:69], v[0:1] op_sel_hi:[1,0]
	v_pk_mul_f32 v[60:61], v[158:159], v[56:57]
	v_pk_mul_f32 v[56:57], v[66:67], v[0:1] op_sel_hi:[1,0]
	v_pk_mul_f32 v[70:71], v[154:155], v[54:55]
	v_pk_mul_f32 v[54:55], v[62:63], v[0:1] op_sel_hi:[1,0]
	v_pk_mul_f32 v[74:75], v[150:151], v[52:53]
	v_pk_mul_f32 v[52:53], v[58:59], v[0:1] op_sel_hi:[1,0]
	v_pk_mul_f32 v[50:51], v[50:51], v[0:1] op_sel_hi:[1,0]
	v_pk_mul_f32 v[64:65], v[156:157], v[64:65]
	v_pk_mul_f32 v[72:73], v[152:153], v[56:57]
	v_pk_mul_f32 v[76:77], v[148:149], v[54:55]
	v_pk_mul_f32 v[78:79], v[146:147], v[50:51]
	v_pk_mul_f32 v[80:81], v[144:145], v[52:53]

;     __device__ __forceinline__ void operator()(const f32x4 (&acc)[2][2][4][2], const Unit& u, int wr, int wc, int fr, int fq, PG8_LAS unsigned char* lds, int& rs_pm, int& rs_tog) const {
;     ...
;                     float q = 0.f;
; #pragma unroll
;                     for (int bj = 0; bj < 2; ++bj)
; #pragma unroll
;                         for (int n = 0; n < 2; ++n) q += (x[bj][n][0] * x[bj][n][0] + x[bj][n][1] * x[bj][n][1]) + (x[bj][n][2] * x[bj][n][2] + x[bj][n][3] * x[bj][n][3]);
;                     q += __shfl_xor(q, 16); q += __shfl_xor(q, 32);
;                     const float rn = __builtin_amdgcn_rsqf(q * (1.0f / 64.0f) + kEps);
; #pragma unroll
;                     for (int bj = 0; bj < 2; ++bj)
; #pragma unroll
;                         for (int n = 0; n < 2; ++n) x[bj][n] = x[bj][n] * rn * gn[bj][n];
.LBB0_184:
	s_andn2_b64 vcc, exec, s[80:81]
	s_cbranch_vccnz .LBB0_186
	v_pk_mul_f32 v[44:45], v[40:41], v[40:41]
	v_pk_mul_f32 v[48:49], v[52:53], v[52:53]
	v_mul_f32_e32 v0, v46, v46
	v_pk_mov_b32 v[54:55], v[48:49], v[44:45] op_sel:[1,0]
	v_mov_b32_e32 v49, v45
	v_pk_add_f32 v[44:45], v[54:55], v[48:49]
	v_pk_mul_f32 v[48:49], v[38:39], v[38:39]
	v_pk_mul_f32 v[54:55], v[50:51], v[50:51]
	v_pk_add_f32 v[44:45], v[44:45], v[44:45] op_sel_hi:[0,1]
	v_pk_mov_b32 v[56:57], v[54:55], v[48:49] op_sel:[1,0]
	v_mov_b32_e32 v55, v49
	v_pk_add_f32 v[48:49], v[56:57], v[54:55]
	v_pk_fma_f32 v[54:55], v[46:47], v[46:47], v[0:1] op_sel_hi:[1,1,0]
	v_mul_f32_e32 v0, v36, v36
	v_pk_add_f32 v[48:49], v[48:49], v[48:49] op_sel_hi:[0,1]
	v_pk_fma_f32 v[56:57], v[36:37], v[36:37], v[0:1] op_sel_hi:[1,1,0]
	v_mul_f32_e32 v54, v42, v42
	v_mul_f32_e32 v56, v43, v43
	v_mul_f32_e32 v44, v34, v34
	v_mul_f32_e32 v48, v35, v35
	v_pk_add_f32 v[54:55], v[54:55], v[56:57]
	v_pk_add_f32 v[44:45], v[44:45], v[48:49]
	s_nop 0
	v_pk_add_f32 v[44:45], v[54:55], v[44:45]
	s_nop 0
	v_add_f32_e32 v0, v44, v45
	v_mov_b32_e32 v44, v0
	s_nop 1
	v_permlane16_swap_b32_e32 v44, v0
	s_nop 1
	v_add_f32_e32 v0, v0, v44
	v_mov_b32_e32 v44, v0
	s_nop 1
	v_permlane32_swap_b32_e32 v44, v0
	s_nop 1
	v_add_f32_e32 v0, v0, v44
	v_fmamk_f32 v0, v0, 0x3c800000, v232
	v_rsq_f32_e32 v0, v0
	s_nop 0
	v_pk_mul_f32 v[40:41], v[40:41], v[0:1] op_sel_hi:[1,0]
	v_pk_mul_f32 v[38:39], v[38:39], v[0:1] op_sel_hi:[1,0]
	v_pk_mul_f32 v[36:37], v[36:37], v[0:1] op_sel_hi:[1,0]
	v_pk_mul_f32 v[48:49], v[52:53], v[0:1] op_sel_hi:[1,0]
	v_pk_mul_f32 v[44:45], v[158:159], v[40:41]
	v_pk_mul_f32 v[40:41], v[50:51], v[0:1] op_sel_hi:[1,0]
	v_pk_mul_f32 v[54:55], v[154:155], v[38:39]
	v_pk_mul_f32 v[38:39], v[46:47], v[0:1] op_sel_hi:[1,0]
	v_pk_mul_f32 v[58:59], v[150:151], v[36:37]
	v_pk_mul_f32 v[36:37], v[42:43], v[0:1] op_sel_hi:[1,0]
	v_pk_mul_f32 v[34:35], v[34:35], v[0:1] op_sel_hi:[1,0]
	v_pk_mul_f32 v[48:49], v[156:157], v[48:49]
	v_pk_mul_f32 v[56:57], v[152:153], v[40:41]
	v_pk_mul_f32 v[60:61], v[148:149], v[38:39]
	v_pk_mul_f32 v[62:63], v[146:147], v[34:35]
	v_pk_mul_f32 v[64:65], v[144:145], v[36:37]

;     __device__ __forceinline__ void operator()(const f32x4 (&acc)[2][2][4][2], const Unit& u, int wr, int wc, int fr, int fq, PG8_LAS unsigned char* lds, int& rs_pm, int& rs_tog) const {
;     ...
;                     float q = 0.f;
; #pragma unroll
;                     for (int bj = 0; bj < 2; ++bj)
; #pragma unroll
;                         for (int n = 0; n < 2; ++n) q += (x[bj][n][0] * x[bj][n][0] + x[bj][n][1] * x[bj][n][1]) + (x[bj][n][2] * x[bj][n][2] + x[bj][n][3] * x[bj][n][3]);
;                     q += __shfl_xor(q, 16); q += __shfl_xor(q, 32);
;                     const float rn = __builtin_amdgcn_rsqf(q * (1.0f / 64.0f) + kEps);
; #pragma unroll
;                     for (int bj = 0; bj < 2; ++bj)
; #pragma unroll
;                         for (int n = 0; n < 2; ++n) x[bj][n] = x[bj][n] * rn * gn[bj][n];
.LBB0_190:
	s_andn2_b64 vcc, exec, s[80:81]
	s_cbranch_vccnz .LBB0_192
	v_pk_mul_f32 v[28:29], v[24:25], v[24:25]
	v_pk_mul_f32 v[32:33], v[36:37], v[36:37]
	v_mul_f32_e32 v0, v30, v30
	v_pk_mov_b32 v[38:39], v[32:33], v[28:29] op_sel:[1,0]
	v_mov_b32_e32 v33, v29
	v_pk_add_f32 v[28:29], v[38:39], v[32:33]
	v_pk_mul_f32 v[32:33], v[22:23], v[22:23]
	v_pk_mul_f32 v[38:39], v[34:35], v[34:35]
	v_pk_add_f32 v[28:29], v[28:29], v[28:29] op_sel_hi:[0,1]
	v_pk_mov_b32 v[40:41], v[38:39], v[32:33] op_sel:[1,0]
	v_mov_b32_e32 v39, v33
	v_pk_add_f32 v[32:33], v[40:41], v[38:39]
	v_pk_fma_f32 v[38:39], v[30:31], v[30:31], v[0:1] op_sel_hi:[1,1,0]
	v_mul_f32_e32 v0, v20, v20
	v_pk_add_f32 v[32:33], v[32:33], v[32:33] op_sel_hi:[0,1]
	v_pk_fma_f32 v[40:41], v[20:21], v[20:21], v[0:1] op_sel_hi:[1,1,0]
	v_mul_f32_e32 v38, v26, v26
	v_mul_f32_e32 v40, v27, v27
	v_mul_f32_e32 v28, v18, v18
	v_mul_f32_e32 v32, v19, v19
	v_pk_add_f32 v[38:39], v[38:39], v[40:41]
	v_pk_add_f32 v[28:29], v[28:29], v[32:33]
	s_nop 0
	v_pk_add_f32 v[28:29], v[38:39], v[28:29]
	s_nop 0
	v_add_f32_e32 v0, v28, v29
	v_mov_b32_e32 v28, v0
	s_nop 1
	v_permlane16_swap_b32_e32 v28, v0
	s_nop 1
	v_add_f32_e32 v0, v0, v28
	v_mov_b32_e32 v28, v0
	s_nop 1
	v_permlane32_swap_b32_e32 v28, v0
	s_nop 1
	v_add_f32_e32 v0, v0, v28
	v_fmamk_f32 v0, v0, 0x3c800000, v232
	v_rsq_f32_e32 v0, v0
	s_nop 0
	v_pk_mul_f32 v[24:25], v[24:25], v[0:1] op_sel_hi:[1,0]
	v_pk_mul_f32 v[22:23], v[22:23], v[0:1] op_sel_hi:[1,0]
	v_pk_mul_f32 v[20:21], v[20:21], v[0:1] op_sel_hi:[1,0]
	v_pk_mul_f32 v[32:33], v[36:37], v[0:1] op_sel_hi:[1,0]
	v_pk_mul_f32 v[28:29], v[158:159], v[24:25]
	v_pk_mul_f32 v[24:25], v[34:35], v[0:1] op_sel_hi:[1,0]
	v_pk_mul_f32 v[38:39], v[154:155], v[22:23]
	v_pk_mul_f32 v[22:23], v[30:31], v[0:1] op_sel_hi:[1,0]
	v_pk_mul_f32 v[42:43], v[150:151], v[20:21]
	v_pk_mul_f32 v[20:21], v[26:27], v[0:1] op_sel_hi:[1,0]
	v_pk_mul_f32 v[18:19], v[18:19], v[0:1] op_sel_hi:[1,0]
	v_pk_mul_f32 v[32:33], v[156:157], v[32:33]
	v_pk_mul_f32 v[40:41], v[152:153], v[24:25]
	v_pk_mul_f32 v[44:45], v[148:149], v[22:23]
	v_pk_mul_f32 v[46:47], v[146:147], v[18:19]
	v_pk_mul_f32 v[48:49], v[144:145], v[20:21]

;     __device__ __forceinline__ void operator()(const f32x4 (&acc)[2][2][4][2], const Unit& u, int wr, int wc, int fr, int fq, PG8_LAS unsigned char* lds, int& rs_pm, int& rs_tog) const {
;     ...
;                     float q = 0.f;
; #pragma unroll
;                     for (int bj = 0; bj < 2; ++bj)
; #pragma unroll
;                         for (int n = 0; n < 2; ++n) q += (x[bj][n][0] * x[bj][n][0] + x[bj][n][1] * x[bj][n][1]) + (x[bj][n][2] * x[bj][n][2] + x[bj][n][3] * x[bj][n][3]);
;                     q += __shfl_xor(q, 16); q += __shfl_xor(q, 32);
;                     const float rn = __builtin_amdgcn_rsqf(q * (1.0f / 64.0f) + kEps);
; #pragma unroll
;                     for (int bj = 0; bj < 2; ++bj)
; #pragma unroll
;                         for (int n = 0; n < 2; ++n) x[bj][n] = x[bj][n] * rn * gn[bj][n];
.LBB0_196:
	s_andn2_b64 vcc, exec, s[46:47]
	s_cbranch_vccnz .LBB0_198
	v_pk_mul_f32 v[14:15], v[8:9], v[8:9]
	v_pk_mul_f32 v[16:17], v[20:21], v[20:21]
	v_mul_f32_e32 v0, v12, v12
	v_pk_mov_b32 v[22:23], v[16:17], v[14:15] op_sel:[1,0]
	v_mov_b32_e32 v17, v15
	v_pk_add_f32 v[14:15], v[22:23], v[16:17]
	v_pk_mul_f32 v[16:17], v[6:7], v[6:7]
	v_pk_mul_f32 v[22:23], v[18:19], v[18:19]
	v_pk_add_f32 v[14:15], v[14:15], v[14:15] op_sel_hi:[0,1]
	v_pk_mov_b32 v[24:25], v[22:23], v[16:17] op_sel:[1,0]
	v_mov_b32_e32 v23, v17
	v_pk_add_f32 v[16:17], v[24:25], v[22:23]
	v_pk_fma_f32 v[22:23], v[12:13], v[12:13], v[0:1] op_sel_hi:[1,1,0]
	v_mul_f32_e32 v0, v4, v4
	v_pk_add_f32 v[16:17], v[16:17], v[16:17] op_sel_hi:[0,1]
	v_pk_fma_f32 v[24:25], v[4:5], v[4:5], v[0:1] op_sel_hi:[1,1,0]
	v_mul_f32_e32 v22, v10, v10
	v_mul_f32_e32 v24, v11, v11
	v_mul_f32_e32 v14, v2, v2
	v_mul_f32_e32 v16, v3, v3
	v_pk_add_f32 v[22:23], v[22:23], v[24:25]
	v_pk_add_f32 v[14:15], v[14:15], v[16:17]
	s_nop 0
	v_pk_add_f32 v[14:15], v[22:23], v[14:15]
	s_nop 0
	v_add_f32_e32 v0, v14, v15
	v_mov_b32_e32 v14, v0
	s_nop 1
	v_permlane16_swap_b32_e32 v14, v0
	s_nop 1
	v_add_f32_e32 v0, v0, v14
	v_mov_b32_e32 v14, v0
	s_nop 1
	v_permlane32_swap_b32_e32 v14, v0
	s_nop 1
	v_add_f32_e32 v0, v0, v14
	v_fmamk_f32 v0, v0, 0x3c800000, v232
	v_rsq_f32_e32 v0, v0
	s_nop 0
	v_pk_mul_f32 v[8:9], v[8:9], v[0:1] op_sel_hi:[1,0]
	v_pk_mul_f32 v[6:7], v[6:7], v[0:1] op_sel_hi:[1,0]
	v_pk_mul_f32 v[4:5], v[4:5], v[0:1] op_sel_hi:[1,0]
	v_pk_mul_f32 v[16:17], v[20:21], v[0:1] op_sel_hi:[1,0]
	v_pk_mul_f32 v[14:15], v[158:159], v[8:9]
	v_pk_mul_f32 v[8:9], v[18:19], v[0:1] op_sel_hi:[1,0]
	v_pk_mul_f32 v[22:23], v[154:155], v[6:7]
	v_pk_mul_f32 v[6:7], v[12:13], v[0:1] op_sel_hi:[1,0]
	v_pk_mul_f32 v[26:27], v[150:151], v[4:5]
	v_pk_mul_f32 v[4:5], v[10:11], v[0:1] op_sel_hi:[1,0]
	v_pk_mul_f32 v[2:3], v[2:3], v[0:1] op_sel_hi:[1,0]
	v_pk_mul_f32 v[16:17], v[156:157], v[16:17]
	v_pk_mul_f32 v[24:25], v[152:153], v[8:9]
	v_pk_mul_f32 v[28:29], v[148:149], v[6:7]
	v_pk_mul_f32 v[30:31], v[146:147], v[2:3]
	v_pk_mul_f32 v[32:33], v[144:145], v[4:5]
